# weight-conversion (convT) loops: the four row loads of a tile issued together with one wait instead of load-wait-write chains
# speedup vs baseline: 1.0278x; 1.0088x over previous
; DI int BIDX() { int b = blockIdx.x; asm volatile("" : "+s"(b)); return b; }
; DI void convT(const float* __restrict__ src, int K, int N, h16* __restrict__ dst, float* tile) {
;     ...
;   for (int t = BIDX(); t < nt; t += gridDim.x) {
;     const int k0 = (t / tn) * 32, n0 = (t % tn) * 32;
; #pragma unroll
;     for (int i = 0; i < 4; ++i) tile[(ty + 8 * i) * 33 + tx] = src[(size_t)(k0 + ty + 8 * i) * N + n0 + tx];
;     __syncthreads();
; #pragma unroll
;     for (int i = 0; i < 4; ++i) dst[(size_t)(n0 + ty + 8 * i) * K + k0 + tx] = (h16)tile[tx * 33 + ty + 8 * i];
;     __syncthreads();
;   }
; DI void conv_weights(const P& p, int l, char* smem) {
;     ...
;   convT(p.in[I_WIN] + (size_t)l * 1024 * 6432, 1024, 6432, W + WO_WIN, tile);
.LBB0_25:
	s_mul_hi_i32 s9, s6, 0x28c1979
	s_lshr_b32 s10, s9, 31
	s_ashr_i32 s9, s9, 1
	s_add_i32 s9, s9, s10
	s_lshl_b32 s10, s9, 5
	s_mulk_i32 s9, 0xe6e0
	s_add_i32 s12, s7, s9
	s_ashr_i32 s13, s12, 31
	v_add_u32_e32 v12, s10, v6
	v_lshl_add_u64 v[8:9], s[12:13], 2, v[2:3]
	v_mad_i64_i32 v[10:11], s[14:15], v12, s17, v[8:9]
	global_load_dword v10, v[10:11], off
	s_ashr_i32 s11, s10, 31
	s_add_i32 s6, s6, s16
	s_add_i32 s7, s7, s8
	s_cmpk_lt_i32 s6, 0x1920
	v_add_u32_e32 v16, 8, v12
	v_mad_i64_i32 v[16:17], s[14:15], v16, s17, v[8:9]
	global_load_dword v16, v[16:17], off
	v_add_u32_e32 v18, 16, v12
	v_mad_i64_i32 v[18:19], s[14:15], v18, s17, v[8:9]
	global_load_dword v18, v[18:19], off
	v_add_u32_e32 v20, 24, v12
	v_mad_i64_i32 v[8:9], s[14:15], v20, s17, v[8:9]
	global_load_dword v8, v[8:9], off
	s_waitcnt vmcnt(0)
	ds_write_b32 v0, v10
	ds_write_b32 v0, v16 offset:1056
	ds_write_b32 v0, v18 offset:2112
	ds_write_b32 v0, v8 offset:3168
	v_lshl_add_u64 v[10:11], s[10:11], 1, v[4:5]
	s_waitcnt lgkmcnt(0)
	s_barrier
	ds_read2_b32 v[12:13], v7 offset1:8
	v_add_u32_e32 v8, s12, v6
	v_ashrrev_i32_e32 v9, 31, v8
	v_lshlrev_b64 v[14:15], 11, v[8:9]
	v_lshl_add_u64 v[14:15], v[10:11], 0, v[14:15]
	s_waitcnt lgkmcnt(0)
	v_cvt_f16_f32_e32 v12, v12
	v_cvt_f16_f32_e32 v9, v13
	global_store_short v[14:15], v12, off
	v_add_u32_e32 v12, 8, v8
	v_ashrrev_i32_e32 v13, 31, v12
	v_lshlrev_b64 v[12:13], 11, v[12:13]
	v_lshl_add_u64 v[12:13], v[10:11], 0, v[12:13]
	global_store_short v[12:13], v9, off
	ds_read2_b32 v[12:13], v7 offset0:16 offset1:24
	v_add_u32_e32 v14, 16, v8
	v_ashrrev_i32_e32 v15, 31, v14
	v_lshlrev_b64 v[14:15], 11, v[14:15]
	v_lshl_add_u64 v[14:15], v[10:11], 0, v[14:15]
	s_waitcnt lgkmcnt(0)
	v_cvt_f16_f32_e32 v9, v12
	v_cvt_f16_f32_e32 v12, v13
	v_add_u32_e32 v8, 24, v8
	global_store_short v[14:15], v9, off
	v_ashrrev_i32_e32 v9, 31, v8
	v_lshlrev_b64 v[8:9], 11, v[8:9]
	v_lshl_add_u64 v[8:9], v[10:11], 0, v[8:9]
	global_store_short v[8:9], v12, off
	s_barrier
	s_cbranch_scc1 .LBB0_25

; DI int BIDX() { int b = blockIdx.x; asm volatile("" : "+s"(b)); return b; }
; DI void convT(const float* __restrict__ src, int K, int N, h16* __restrict__ dst, float* tile) {
;     ...
;   for (int t = BIDX(); t < nt; t += gridDim.x) {
;     const int k0 = (t / tn) * 32, n0 = (t % tn) * 32;
; #pragma unroll
;     for (int i = 0; i < 4; ++i) tile[(ty + 8 * i) * 33 + tx] = src[(size_t)(k0 + ty + 8 * i) * N + n0 + tx];
;     __syncthreads();
; #pragma unroll
;     for (int i = 0; i < 4; ++i) dst[(size_t)(n0 + ty + 8 * i) * K + k0 + tx] = (h16)tile[tx * 33 + ty + 8 * i];
;     __syncthreads();
;   }
; DI void conv_weights(const P& p, int l, char* smem) {
;     ...
;   convT(p.in[I_WUQ] + (size_t)l * 384 * 768, 384, 768, W + WO_UQ, tile);
.LBB0_28:
	s_mul_hi_i32 s9, s6, 0x2aaaaaab
	s_lshr_b32 s10, s9, 31
	s_ashr_i32 s9, s9, 2
	s_add_i32 s9, s9, s10
	s_lshl_b32 s10, s9, 5
	s_mulk_i32 s9, 0xfd00
	s_add_i32 s12, s7, s9
	s_ashr_i32 s13, s12, 31
	v_add_u32_e32 v12, s10, v6
	v_lshl_add_u64 v[8:9], s[12:13], 2, v[2:3]
	v_mad_i64_i32 v[10:11], s[14:15], v12, s3, v[8:9]
	global_load_dword v10, v[10:11], off
	s_ashr_i32 s11, s10, 31
	v_add_u32_e32 v14, s12, v6
	s_add_i32 s6, s6, s16
	s_add_i32 s7, s7, s8
	s_cmpk_lt_i32 s6, 0x120
	v_add_u32_e32 v16, 8, v12
	v_mad_i64_i32 v[16:17], s[14:15], v16, s3, v[8:9]
	global_load_dword v16, v[16:17], off
	v_add_u32_e32 v18, 16, v12
	v_mad_i64_i32 v[18:19], s[14:15], v18, s3, v[8:9]
	global_load_dword v18, v[18:19], off
	v_add_u32_e32 v20, 24, v12
	v_mad_i64_i32 v[8:9], s[14:15], v20, s3, v[8:9]
	global_load_dword v8, v[8:9], off
	s_waitcnt vmcnt(0)
	ds_write_b32 v0, v10
	ds_write_b32 v0, v16 offset:1056
	ds_write_b32 v0, v18 offset:2112
	ds_write_b32 v0, v8 offset:3168
	s_waitcnt lgkmcnt(0)
	s_barrier
	ds_read2_b32 v[10:11], v7 offset1:8
	v_lshl_add_u64 v[8:9], s[10:11], 1, v[4:5]
	v_mad_i64_i32 v[12:13], s[10:11], v14, s2, v[8:9]
	s_waitcnt lgkmcnt(0)
	v_cvt_f16_f32_e32 v10, v10
	global_store_short v[12:13], v10, off
	v_cvt_f16_f32_e32 v12, v11
	v_add_u32_e32 v10, 8, v14
	v_mad_i64_i32 v[10:11], s[10:11], v10, s2, v[8:9]
	global_store_short v[10:11], v12, off
	ds_read2_b32 v[10:11], v7 offset0:16 offset1:24
	v_add_u32_e32 v12, 16, v14
	v_mad_i64_i32 v[12:13], s[10:11], v12, s2, v[8:9]
	s_waitcnt lgkmcnt(0)
	v_cvt_f16_f32_e32 v10, v10
	global_store_short v[12:13], v10, off
	v_cvt_f16_f32_e32 v10, v11
	v_add_u32_e32 v11, 24, v14
	v_mad_i64_i32 v[8:9], s[10:11], v11, s2, v[8:9]
	global_store_short v[8:9], v10, off
	s_barrier
	s_cbranch_scc1 .LBB0_28

; DI int BIDX() { int b = blockIdx.x; asm volatile("" : "+s"(b)); return b; }
; DI void convT(const float* __restrict__ src, int K, int N, h16* __restrict__ dst, float* tile) {
;     ...
;   for (int t = BIDX(); t < nt; t += gridDim.x) {
;     const int k0 = (t / tn) * 32, n0 = (t % tn) * 32;
; #pragma unroll
;     for (int i = 0; i < 4; ++i) tile[(ty + 8 * i) * 33 + tx] = src[(size_t)(k0 + ty + 8 * i) * N + n0 + tx];
;     __syncthreads();
; #pragma unroll
;     for (int i = 0; i < 4; ++i) dst[(size_t)(n0 + ty + 8 * i) * K + k0 + tx] = (h16)tile[tx * 33 + ty + 8 * i];
;     __syncthreads();
;   }
; DI void conv_weights(const P& p, int l, char* smem) {
;     ...
;   convT(p.in[I_WUKV] + (size_t)l * 256 * 1024, 256, 1024, W + WO_UKV, tile);
.LBB0_31:
	s_ashr_i32 s6, s8, 31
	s_lshr_b32 s6, s6, 27
	s_add_i32 s7, s8, s6
	s_and_b32 s6, s7, 0xffffffe0
	s_lshl_b32 s7, s7, 5
	s_and_b32 s7, s7, 0xfffffc00
	s_sub_i32 s12, s9, s7
	v_add_u32_e32 v8, s6, v6
	s_ashr_i32 s13, s12, 31
	v_ashrrev_i32_e32 v9, 31, v8
	v_lshl_add_u64 v[10:11], s[12:13], 2, v[2:3]
	v_lshlrev_b64 v[8:9], 12, v[8:9]
	v_lshl_add_u64 v[8:9], v[10:11], 0, v[8:9]
	global_load_dword v16, v[8:9], off
	s_ashr_i32 s7, s6, 31
	s_add_i32 s8, s8, s16
	s_add_i32 s9, s9, s10
	s_cmpk_lt_i32 s8, 0x100
	v_add_co_u32_e32 v18, vcc, s87, v8
	s_nop 1
	v_addc_co_u32_e32 v19, vcc, 0, v9, vcc
	global_load_dword v18, v[18:19], off
	v_add_co_u32_e32 v10, vcc, s2, v8
	s_nop 1
	v_addc_co_u32_e32 v11, vcc, 0, v9, vcc
	v_add_co_u32_e32 v8, vcc, s3, v8
	global_load_dword v10, v[10:11], off
	s_nop 0
	v_addc_co_u32_e32 v9, vcc, 0, v9, vcc
	global_load_dword v8, v[8:9], off
	s_waitcnt vmcnt(0)
	ds_write_b32 v0, v16
	ds_write_b32 v0, v18 offset:1056
	ds_write_b32 v0, v10 offset:2112
	ds_write_b32 v0, v8 offset:3168
	v_lshl_add_u64 v[10:11], s[6:7], 1, v[4:5]
	s_waitcnt lgkmcnt(0)
	s_barrier
	ds_read2_b32 v[12:13], v7 offset1:8
	v_add_u32_e32 v8, s12, v6
	v_ashrrev_i32_e32 v9, 31, v8
	v_lshlrev_b64 v[14:15], 9, v[8:9]
	v_lshl_add_u64 v[14:15], v[10:11], 0, v[14:15]
	s_waitcnt lgkmcnt(0)
	v_cvt_f16_f32_e32 v12, v12
	v_cvt_f16_f32_e32 v9, v13
	global_store_short v[14:15], v12, off
	v_add_u32_e32 v12, 8, v8
	v_ashrrev_i32_e32 v13, 31, v12
	v_lshlrev_b64 v[12:13], 9, v[12:13]
	v_lshl_add_u64 v[12:13], v[10:11], 0, v[12:13]
	global_store_short v[12:13], v9, off
	ds_read2_b32 v[12:13], v7 offset0:16 offset1:24
	v_add_u32_e32 v14, 16, v8
	v_ashrrev_i32_e32 v15, 31, v14
	v_lshlrev_b64 v[14:15], 9, v[14:15]
	v_lshl_add_u64 v[14:15], v[10:11], 0, v[14:15]
	s_waitcnt lgkmcnt(0)
	v_cvt_f16_f32_e32 v9, v12
	v_cvt_f16_f32_e32 v12, v13
	v_add_u32_e32 v8, 24, v8
	global_store_short v[14:15], v9, off
	v_ashrrev_i32_e32 v9, 31, v8
	v_lshlrev_b64 v[8:9], 9, v[8:9]
	v_lshl_add_u64 v[8:9], v[10:11], 0, v[8:9]
	global_store_short v[8:9], v12, off
	s_barrier
	s_cbranch_scc1 .LBB0_31

; DI int BIDX() { int b = blockIdx.x; asm volatile("" : "+s"(b)); return b; }
; DI void convT(const float* __restrict__ src, int K, int N, h16* __restrict__ dst, float* tile) {
;     ...
;   for (int t = BIDX(); t < nt; t += gridDim.x) {
;     const int k0 = (t / tn) * 32, n0 = (t % tn) * 32;
; #pragma unroll
;     for (int i = 0; i < 4; ++i) tile[(ty + 8 * i) * 33 + tx] = src[(size_t)(k0 + ty + 8 * i) * N + n0 + tx];
;     __syncthreads();
; #pragma unroll
;     for (int i = 0; i < 4; ++i) dst[(size_t)(n0 + ty + 8 * i) * K + k0 + tx] = (h16)tile[tx * 33 + ty + 8 * i];
;     __syncthreads();
;   }
; DI void conv_weights(const P& p, int l, char* smem) {
;     ...
;   convT(p.in[I_G2] + (size_t)l * 128 * 512, 128, 512, W + WO_G2, tile);
.LBB0_34:
	s_ashr_i32 s9, s6, 31
	s_lshr_b32 s9, s9, 28
	s_add_i32 s9, s6, s9
	s_ashr_i32 s9, s9, 4
	s_lshl_b32 s10, s9, 5
	s_lshl_b32 s9, s9, 9
	s_sub_i32 s12, s7, s9
	v_add_u32_e32 v8, s10, v6
	s_ashr_i32 s13, s12, 31
	v_ashrrev_i32_e32 v9, 31, v8
	v_lshl_add_u64 v[10:11], s[12:13], 2, v[2:3]
	v_lshlrev_b64 v[8:9], 11, v[8:9]
	v_lshl_add_u64 v[8:9], v[10:11], 0, v[8:9]
	global_load_dword v16, v[8:9], off
	s_ashr_i32 s11, s10, 31
	s_add_i32 s6, s6, s16
	s_add_i32 s7, s7, s8
	s_cmp_lt_i32 s6, 64
	v_add_co_u32_e32 v18, vcc, s2, v8
	s_nop 1
	v_addc_co_u32_e32 v19, vcc, 0, v9, vcc
	global_load_dword v18, v[18:19], off
	v_add_co_u32_e32 v10, vcc, s87, v8
	s_nop 1
	v_addc_co_u32_e32 v11, vcc, 0, v9, vcc
	v_add_co_u32_e32 v8, vcc, s14, v8
	global_load_dword v10, v[10:11], off
	s_nop 0
	v_addc_co_u32_e32 v9, vcc, 0, v9, vcc
	global_load_dword v8, v[8:9], off
	s_waitcnt vmcnt(0)
	ds_write_b32 v0, v16
	ds_write_b32 v0, v18 offset:1056
	ds_write_b32 v0, v10 offset:2112
	ds_write_b32 v0, v8 offset:3168
	v_lshl_add_u64 v[10:11], s[10:11], 1, v[4:5]
	s_waitcnt lgkmcnt(0)
	s_barrier
	ds_read2_b32 v[12:13], v7 offset1:8
	v_add_u32_e32 v8, s12, v6
	v_ashrrev_i32_e32 v9, 31, v8
	v_lshlrev_b64 v[14:15], 8, v[8:9]
	v_lshl_add_u64 v[14:15], v[10:11], 0, v[14:15]
	s_waitcnt lgkmcnt(0)
	v_cvt_f16_f32_e32 v12, v12
	v_cvt_f16_f32_e32 v9, v13
	global_store_short v[14:15], v12, off
	v_add_u32_e32 v12, 8, v8
	v_ashrrev_i32_e32 v13, 31, v12
	v_lshlrev_b64 v[12:13], 8, v[12:13]
	v_lshl_add_u64 v[12:13], v[10:11], 0, v[12:13]
	global_store_short v[12:13], v9, off
	ds_read2_b32 v[12:13], v7 offset0:16 offset1:24
	v_add_u32_e32 v14, 16, v8
	v_ashrrev_i32_e32 v15, 31, v14
	v_lshlrev_b64 v[14:15], 8, v[14:15]
	v_lshl_add_u64 v[14:15], v[10:11], 0, v[14:15]
	s_waitcnt lgkmcnt(0)
	v_cvt_f16_f32_e32 v9, v12
	v_cvt_f16_f32_e32 v12, v13
	v_add_u32_e32 v8, 24, v8
	global_store_short v[14:15], v9, off
	v_ashrrev_i32_e32 v9, 31, v8
	v_lshlrev_b64 v[8:9], 8, v[8:9]
	v_lshl_add_u64 v[8:9], v[10:11], 0, v[8:9]
	global_store_short v[8:9], v12, off
	s_barrier
	s_cbranch_scc1 .LBB0_34

; DI int BIDX() { int b = blockIdx.x; asm volatile("" : "+s"(b)); return b; }
; DI void convT(const float* __restrict__ src, int K, int N, h16* __restrict__ dst, float* tile) {
;     ...
;   for (int t = BIDX(); t < nt; t += gridDim.x) {
;     const int k0 = (t / tn) * 32, n0 = (t % tn) * 32;
; #pragma unroll
;     for (int i = 0; i < 4; ++i) tile[(ty + 8 * i) * 33 + tx] = src[(size_t)(k0 + ty + 8 * i) * N + n0 + tx];
;     __syncthreads();
; #pragma unroll
;     for (int i = 0; i < 4; ++i) dst[(size_t)(n0 + ty + 8 * i) * K + k0 + tx] = (h16)tile[tx * 33 + ty + 8 * i];
;     __syncthreads();
;   }
; DI void conv_weights(const P& p, int l, char* smem) {
;     ...
;   for (int n = 0; n < 3; ++n) convT(p.in[I_WB] + ((size_t)l * 3 + n) * 512 * 1024, 512, 1024, W + WO_WB + (size_t)n * 1024 * 512, tile);
.LBB0_37:
	s_ashr_i32 s6, s8, 31
	s_lshr_b32 s6, s6, 27
	s_add_i32 s7, s8, s6
	s_and_b32 s6, s7, 0xffffffe0
	s_lshl_b32 s7, s7, 5
	s_and_b32 s7, s7, 0xfffffc00
	s_sub_i32 s12, s9, s7
	v_add_u32_e32 v8, s6, v6
	s_ashr_i32 s13, s12, 31
	v_ashrrev_i32_e32 v9, 31, v8
	v_lshl_add_u64 v[10:11], s[12:13], 2, v[2:3]
	v_lshlrev_b64 v[8:9], 12, v[8:9]
	v_lshl_add_u64 v[8:9], v[10:11], 0, v[8:9]
	global_load_dword v16, v[8:9], off
	s_ashr_i32 s7, s6, 31
	s_add_i32 s8, s8, s16
	s_add_i32 s9, s9, s10
	s_cmpk_lt_i32 s8, 0x200
	v_add_co_u32_e32 v18, vcc, s87, v8
	s_nop 1
	v_addc_co_u32_e32 v19, vcc, 0, v9, vcc
	global_load_dword v18, v[18:19], off
	v_add_co_u32_e32 v10, vcc, s2, v8
	s_nop 1
	v_addc_co_u32_e32 v11, vcc, 0, v9, vcc
	v_add_co_u32_e32 v8, vcc, s3, v8
	global_load_dword v10, v[10:11], off
	s_nop 0
	v_addc_co_u32_e32 v9, vcc, 0, v9, vcc
	global_load_dword v8, v[8:9], off
	s_waitcnt vmcnt(0)
	ds_write_b32 v0, v16
	ds_write_b32 v0, v18 offset:1056
	ds_write_b32 v0, v10 offset:2112
	ds_write_b32 v0, v8 offset:3168
	v_lshl_add_u64 v[10:11], s[6:7], 1, v[4:5]
	s_waitcnt lgkmcnt(0)
	s_barrier
	ds_read2_b32 v[12:13], v7 offset1:8
	v_add_u32_e32 v8, s12, v6
	v_ashrrev_i32_e32 v9, 31, v8
	v_lshlrev_b64 v[14:15], 10, v[8:9]
	v_lshl_add_u64 v[14:15], v[10:11], 0, v[14:15]
	s_waitcnt lgkmcnt(0)
	v_cvt_f16_f32_e32 v12, v12
	v_cvt_f16_f32_e32 v9, v13
	global_store_short v[14:15], v12, off
	v_add_u32_e32 v12, 8, v8
	v_ashrrev_i32_e32 v13, 31, v12
	v_lshlrev_b64 v[12:13], 10, v[12:13]
	v_lshl_add_u64 v[12:13], v[10:11], 0, v[12:13]
	global_store_short v[12:13], v9, off
	ds_read2_b32 v[12:13], v7 offset0:16 offset1:24
	v_add_u32_e32 v14, 16, v8
	v_ashrrev_i32_e32 v15, 31, v14
	v_lshlrev_b64 v[14:15], 10, v[14:15]
	v_lshl_add_u64 v[14:15], v[10:11], 0, v[14:15]
	s_waitcnt lgkmcnt(0)
	v_cvt_f16_f32_e32 v9, v12
	v_cvt_f16_f32_e32 v12, v13
	v_add_u32_e32 v8, 24, v8
	global_store_short v[14:15], v9, off
	v_ashrrev_i32_e32 v9, 31, v8
	v_lshlrev_b64 v[8:9], 10, v[8:9]
	v_lshl_add_u64 v[8:9], v[10:11], 0, v[8:9]
	global_store_short v[8:9], v12, off
	s_barrier
	s_cbranch_scc1 .LBB0_37

; DI int BIDX() { int b = blockIdx.x; asm volatile("" : "+s"(b)); return b; }
; DI void convT(const float* __restrict__ src, int K, int N, h16* __restrict__ dst, float* tile) {
;     ...
;   for (int t = BIDX(); t < nt; t += gridDim.x) {
;     const int k0 = (t / tn) * 32, n0 = (t % tn) * 32;
; #pragma unroll
;     for (int i = 0; i < 4; ++i) tile[(ty + 8 * i) * 33 + tx] = src[(size_t)(k0 + ty + 8 * i) * N + n0 + tx];
;     __syncthreads();
; #pragma unroll
;     for (int i = 0; i < 4; ++i) dst[(size_t)(n0 + ty + 8 * i) * K + k0 + tx] = (h16)tile[tx * 33 + ty + 8 * i];
;     __syncthreads();
;   }
; DI void conv_weights(const P& p, int l, char* smem) {
;     ...
;   convT(p.in[I_WOUT] + (size_t)l * 1024 * 1024, 1024, 1024, W + WO_WOUT, tile);
.LBB0_46:
	s_ashr_i32 s6, s8, 31
	s_lshr_b32 s6, s6, 27
	s_add_i32 s7, s8, s6
	s_and_b32 s6, s7, 0xffffffe0
	s_lshl_b32 s7, s7, 5
	s_and_b32 s7, s7, 0xfffffc00
	s_sub_i32 s12, s9, s7
	v_add_u32_e32 v8, s6, v6
	s_ashr_i32 s13, s12, 31
	v_ashrrev_i32_e32 v9, 31, v8
	v_lshl_add_u64 v[10:11], s[12:13], 2, v[2:3]
	v_lshlrev_b64 v[8:9], 12, v[8:9]
	v_lshl_add_u64 v[8:9], v[10:11], 0, v[8:9]
	global_load_dword v16, v[8:9], off
	s_ashr_i32 s7, s6, 31
	s_add_i32 s8, s8, s16
	s_add_i32 s9, s9, s10
	s_cmpk_lt_i32 s8, 0x400
	v_add_co_u32_e32 v18, vcc, s87, v8
	s_nop 1
	v_addc_co_u32_e32 v19, vcc, 0, v9, vcc
	global_load_dword v18, v[18:19], off
	v_add_co_u32_e32 v10, vcc, s2, v8
	s_nop 1
	v_addc_co_u32_e32 v11, vcc, 0, v9, vcc
	v_add_co_u32_e32 v8, vcc, s3, v8
	global_load_dword v10, v[10:11], off
	s_nop 0
	v_addc_co_u32_e32 v9, vcc, 0, v9, vcc
	global_load_dword v8, v[8:9], off
	s_waitcnt vmcnt(0)
	ds_write_b32 v0, v16
	ds_write_b32 v0, v18 offset:1056
	ds_write_b32 v0, v10 offset:2112
	ds_write_b32 v0, v8 offset:3168
	v_lshl_add_u64 v[10:11], s[6:7], 1, v[4:5]
	s_waitcnt lgkmcnt(0)
	s_barrier
	ds_read2_b32 v[12:13], v7 offset1:8
	v_add_u32_e32 v8, s12, v6
	v_ashrrev_i32_e32 v9, 31, v8
	v_lshlrev_b64 v[14:15], 11, v[8:9]
	v_lshl_add_u64 v[14:15], v[10:11], 0, v[14:15]
	s_waitcnt lgkmcnt(0)
	v_cvt_f16_f32_e32 v12, v12
	v_cvt_f16_f32_e32 v9, v13
	global_store_short v[14:15], v12, off
	v_add_u32_e32 v12, 8, v8
	v_ashrrev_i32_e32 v13, 31, v12
	v_lshlrev_b64 v[12:13], 11, v[12:13]
	v_lshl_add_u64 v[12:13], v[10:11], 0, v[12:13]
	global_store_short v[12:13], v9, off
	ds_read2_b32 v[12:13], v7 offset0:16 offset1:24
	v_add_u32_e32 v14, 16, v8
	v_ashrrev_i32_e32 v15, 31, v14
	v_lshlrev_b64 v[14:15], 11, v[14:15]
	v_lshl_add_u64 v[14:15], v[10:11], 0, v[14:15]
	s_waitcnt lgkmcnt(0)
	v_cvt_f16_f32_e32 v9, v12
	v_cvt_f16_f32_e32 v12, v13
	v_add_u32_e32 v8, 24, v8
	global_store_short v[14:15], v9, off
	v_ashrrev_i32_e32 v9, 31, v8
	v_lshlrev_b64 v[8:9], 11, v[8:9]
	v_lshl_add_u64 v[8:9], v[10:11], 0, v[8:9]
	global_store_short v[8:9], v12, off
	s_barrier
	s_cbranch_scc1 .LBB0_46

; DI int BIDX() { int b = blockIdx.x; asm volatile("" : "+s"(b)); return b; }
; DI void convT(const float* __restrict__ src, int K, int N, h16* __restrict__ dst, float* tile) {
;     ...
;   for (int t = BIDX(); t < nt; t += gridDim.x) {
;     const int k0 = (t / tn) * 32, n0 = (t % tn) * 32;
; #pragma unroll
;     for (int i = 0; i < 4; ++i) tile[(ty + 8 * i) * 33 + tx] = src[(size_t)(k0 + ty + 8 * i) * N + n0 + tx];
;     __syncthreads();
; #pragma unroll
;     for (int i = 0; i < 4; ++i) dst[(size_t)(n0 + ty + 8 * i) * K + k0 + tx] = (h16)tile[tx * 33 + ty + 8 * i];
;     __syncthreads();
;   }
; DI void conv_weights(const P& p, int l, char* smem) {
;     ...
;   convT(p.in[I_FIN] + (size_t)l * 1024 * 5632, 1024, 5632, W + WO_FIN, tile);
.LBB0_49:
	s_mul_hi_i32 s9, s6, 0x2e8ba2e9
	s_lshr_b32 s10, s9, 31
	s_ashr_i32 s9, s9, 5
	s_add_i32 s9, s9, s10
	s_lshl_b32 s10, s9, 5
	s_mulk_i32 s9, 0xea00
	s_add_i32 s12, s7, s9
	s_ashr_i32 s13, s12, 31
	v_add_u32_e32 v12, s10, v6
	v_lshl_add_u64 v[8:9], s[12:13], 2, v[2:3]
	v_mad_i64_i32 v[10:11], s[14:15], v12, s2, v[8:9]
	global_load_dword v10, v[10:11], off
	s_ashr_i32 s11, s10, 31
	s_add_i32 s6, s6, s16
	s_add_i32 s7, s7, s8
	s_cmpk_lt_i32 s6, 0x1600
	v_add_u32_e32 v16, 8, v12
	v_mad_i64_i32 v[16:17], s[14:15], v16, s2, v[8:9]
	global_load_dword v16, v[16:17], off
	v_add_u32_e32 v18, 16, v12
	v_mad_i64_i32 v[18:19], s[14:15], v18, s2, v[8:9]
	global_load_dword v18, v[18:19], off
	v_add_u32_e32 v20, 24, v12
	v_mad_i64_i32 v[8:9], s[14:15], v20, s2, v[8:9]
	global_load_dword v8, v[8:9], off
	s_waitcnt vmcnt(0)
	ds_write_b32 v0, v10
	ds_write_b32 v0, v16 offset:1056
	ds_write_b32 v0, v18 offset:2112
	ds_write_b32 v0, v8 offset:3168
	v_lshl_add_u64 v[10:11], s[10:11], 1, v[4:5]
	s_waitcnt lgkmcnt(0)
	s_barrier
	ds_read2_b32 v[12:13], v7 offset1:8
	v_add_u32_e32 v8, s12, v6
	v_ashrrev_i32_e32 v9, 31, v8
	v_lshlrev_b64 v[14:15], 11, v[8:9]
	v_lshl_add_u64 v[14:15], v[10:11], 0, v[14:15]
	s_waitcnt lgkmcnt(0)
	v_cvt_f16_f32_e32 v12, v12
	v_cvt_f16_f32_e32 v9, v13
	global_store_short v[14:15], v12, off
	v_add_u32_e32 v12, 8, v8
	v_ashrrev_i32_e32 v13, 31, v12
	v_lshlrev_b64 v[12:13], 11, v[12:13]
	v_lshl_add_u64 v[12:13], v[10:11], 0, v[12:13]
	global_store_short v[12:13], v9, off
	ds_read2_b32 v[12:13], v7 offset0:16 offset1:24
	v_add_u32_e32 v14, 16, v8
	v_ashrrev_i32_e32 v15, 31, v14
	v_lshlrev_b64 v[14:15], 11, v[14:15]
	v_lshl_add_u64 v[14:15], v[10:11], 0, v[14:15]
	s_waitcnt lgkmcnt(0)
	v_cvt_f16_f32_e32 v9, v12
	v_cvt_f16_f32_e32 v12, v13
	v_add_u32_e32 v8, 24, v8
	global_store_short v[14:15], v9, off
	v_ashrrev_i32_e32 v9, 31, v8
	v_lshlrev_b64 v[8:9], 11, v[8:9]
	v_lshl_add_u64 v[8:9], v[10:11], 0, v[8:9]
	global_store_short v[8:9], v12, off
	s_barrier
	s_cbranch_scc1 .LBB0_49

; DI int BIDX() { int b = blockIdx.x; asm volatile("" : "+s"(b)); return b; }
; DI void convT(const float* __restrict__ src, int K, int N, h16* __restrict__ dst, float* tile) {
;     ...
;   for (int t = BIDX(); t < nt; t += gridDim.x) {
;     const int k0 = (t / tn) * 32, n0 = (t % tn) * 32;
; #pragma unroll
;     for (int i = 0; i < 4; ++i) tile[(ty + 8 * i) * 33 + tx] = src[(size_t)(k0 + ty + 8 * i) * N + n0 + tx];
;     __syncthreads();
; #pragma unroll
;     for (int i = 0; i < 4; ++i) dst[(size_t)(n0 + ty + 8 * i) * K + k0 + tx] = (h16)tile[tx * 33 + ty + 8 * i];
;     __syncthreads();
;   }
; DI void conv_weights(const P& p, int l, char* smem) {
;     ...
;   convT(p.in[I_FOUT] + (size_t)l * 2816 * 1024, 2816, 1024, W + WO_FOUT, tile);
.LBB0_52:
	s_ashr_i32 s6, s8, 31
	s_lshr_b32 s6, s6, 27
	s_add_i32 s7, s8, s6
	s_and_b32 s6, s7, 0xffffffe0
	s_lshl_b32 s7, s7, 5
	s_and_b32 s7, s7, 0xfffffc00
	s_sub_i32 s12, s9, s7
	v_add_u32_e32 v8, s6, v6
	s_ashr_i32 s13, s12, 31
	v_ashrrev_i32_e32 v9, 31, v8
	v_lshl_add_u64 v[10:11], s[12:13], 2, v[2:3]
	v_lshlrev_b64 v[8:9], 12, v[8:9]
	v_lshl_add_u64 v[8:9], v[10:11], 0, v[8:9]
	global_load_dword v16, v[8:9], off
	s_mov_b32 s2, 0x10000
	s_ashr_i32 s7, s6, 31
	v_add_u32_e32 v14, s12, v6
	s_add_i32 s8, s8, s16
	s_add_i32 s9, s9, s10
	s_cmpk_gt_i32 s8, 0xaff
	v_add_co_u32_e32 v18, vcc, s87, v8
	s_nop 1
	v_addc_co_u32_e32 v19, vcc, 0, v9, vcc
	global_load_dword v18, v[18:19], off
	v_add_co_u32_e32 v10, vcc, s2, v8
	s_mov_b32 s2, 0x18000
	s_nop 0
	v_addc_co_u32_e32 v11, vcc, 0, v9, vcc
	v_add_co_u32_e32 v8, vcc, s2, v8
	global_load_dword v10, v[10:11], off
	s_nop 0
	v_addc_co_u32_e32 v9, vcc, 0, v9, vcc
	global_load_dword v8, v[8:9], off
	s_movk_i32 s2, 0x1600
	s_waitcnt vmcnt(0)
	ds_write_b32 v0, v16
	ds_write_b32 v0, v18 offset:1056
	ds_write_b32 v0, v10 offset:2112
	ds_write_b32 v0, v8 offset:3168
	s_waitcnt lgkmcnt(0)
	s_barrier
	ds_read2_b32 v[10:11], v7 offset1:8
	v_lshl_add_u64 v[8:9], s[6:7], 1, v[4:5]
	v_mad_i64_i32 v[12:13], s[6:7], v14, s2, v[8:9]
	s_waitcnt lgkmcnt(0)
	v_cvt_f16_f32_e32 v10, v10
	global_store_short v[12:13], v10, off
	v_cvt_f16_f32_e32 v12, v11
	v_add_u32_e32 v10, 8, v14
	v_mad_i64_i32 v[10:11], s[6:7], v10, s2, v[8:9]
	global_store_short v[10:11], v12, off
	ds_read2_b32 v[10:11], v7 offset0:16 offset1:24
	v_add_u32_e32 v12, 16, v14
	v_mad_i64_i32 v[12:13], s[6:7], v12, s2, v[8:9]
	s_waitcnt lgkmcnt(0)
	v_cvt_f16_f32_e32 v10, v10
	global_store_short v[12:13], v10, off
	v_cvt_f16_f32_e32 v10, v11
	v_add_u32_e32 v11, 24, v14
	v_mad_i64_i32 v[8:9], s[6:7], v11, s2, v[8:9]
	global_store_short v[8:9], v10, off
	s_barrier
	s_cbranch_scc0 .LBB0_52

; DI int BIDX() { int b = blockIdx.x; asm volatile("" : "+s"(b)); return b; }
; DI void convT(const float* __restrict__ src, int K, int N, h16* __restrict__ dst, float* tile) {
;     ...
;   for (int t = BIDX(); t < nt; t += gridDim.x) {
;     const int k0 = (t / tn) * 32, n0 = (t % tn) * 32;
; #pragma unroll
;     for (int i = 0; i < 4; ++i) tile[(ty + 8 * i) * 33 + tx] = src[(size_t)(k0 + ty + 8 * i) * N + n0 + tx];
;     __syncthreads();
; #pragma unroll
;     for (int i = 0; i < 4; ++i) dst[(size_t)(n0 + ty + 8 * i) * K + k0 + tx] = (h16)tile[tx * 33 + ty + 8 * i];
;     __syncthreads();
;   }
; DI void conv_weights(const P& p, int l, char* smem) {
;     ...
;   convT(p.in[I_WIN] + (size_t)l * 1024 * 6432, 1024, 6432, W + WO_WIN, tile);
.LBB0_2014:
	s_mul_hi_i32 s4, s0, 0x28c1979
	s_lshr_b32 s5, s4, 31
	s_ashr_i32 s4, s4, 1
	s_add_i32 s5, s4, s5
	s_lshl_b32 s4, s5, 5
	s_mulk_i32 s5, 0xe6e0
	s_add_i32 s6, s1, s5
	s_ashr_i32 s7, s6, 31
	v_add_u32_e32 v12, s4, v6
	v_lshl_add_u64 v[8:9], s[6:7], 2, v[2:3]
	v_mad_i64_i32 v[10:11], s[8:9], v12, s3, v[8:9]
	global_load_dword v10, v[10:11], off
	s_ashr_i32 s5, s4, 31
	s_add_i32 s0, s0, s72
	s_add_i32 s1, s1, s2
	s_cmpk_lt_i32 s0, 0x1920
	v_add_u32_e32 v16, 8, v12
	v_mad_i64_i32 v[16:17], s[8:9], v16, s3, v[8:9]
	global_load_dword v16, v[16:17], off
	v_add_u32_e32 v18, 16, v12
	v_mad_i64_i32 v[18:19], s[8:9], v18, s3, v[8:9]
	global_load_dword v18, v[18:19], off
	v_add_u32_e32 v20, 24, v12
	v_mad_i64_i32 v[8:9], s[8:9], v20, s3, v[8:9]
	global_load_dword v8, v[8:9], off
	s_waitcnt vmcnt(0)
	ds_write_b32 v0, v10
	ds_write_b32 v0, v16 offset:1056
	ds_write_b32 v0, v18 offset:2112
	ds_write_b32 v0, v8 offset:3168
	v_lshl_add_u64 v[10:11], s[4:5], 1, v[4:5]
	s_waitcnt lgkmcnt(0)
	s_barrier
	ds_read2_b32 v[12:13], v7 offset1:8
	v_add_u32_e32 v8, s6, v6
	v_ashrrev_i32_e32 v9, 31, v8
	v_lshlrev_b64 v[14:15], 11, v[8:9]
	v_lshl_add_u64 v[14:15], v[10:11], 0, v[14:15]
	s_waitcnt lgkmcnt(0)
	v_cvt_f16_f32_e32 v12, v12
	v_cvt_f16_f32_e32 v9, v13
	global_store_short v[14:15], v12, off
	v_add_u32_e32 v12, 8, v8
	v_ashrrev_i32_e32 v13, 31, v12
	v_lshlrev_b64 v[12:13], 11, v[12:13]
	v_lshl_add_u64 v[12:13], v[10:11], 0, v[12:13]
	global_store_short v[12:13], v9, off
	ds_read2_b32 v[12:13], v7 offset0:16 offset1:24
	v_add_u32_e32 v14, 16, v8
	v_ashrrev_i32_e32 v15, 31, v14
	v_lshlrev_b64 v[14:15], 11, v[14:15]
	v_lshl_add_u64 v[14:15], v[10:11], 0, v[14:15]
	s_waitcnt lgkmcnt(0)
	v_cvt_f16_f32_e32 v9, v12
	v_cvt_f16_f32_e32 v12, v13
	v_add_u32_e32 v8, 24, v8
	global_store_short v[14:15], v9, off
	v_ashrrev_i32_e32 v9, 31, v8
	v_lshlrev_b64 v[8:9], 11, v[8:9]
	v_lshl_add_u64 v[8:9], v[10:11], 0, v[8:9]
	global_store_short v[8:9], v12, off
	s_barrier
	s_cbranch_scc1 .LBB0_2014

; DI int BIDX() { int b = blockIdx.x; asm volatile("" : "+s"(b)); return b; }
; DI void convT(const float* __restrict__ src, int K, int N, h16* __restrict__ dst, float* tile) {
;     ...
;   for (int t = BIDX(); t < nt; t += gridDim.x) {
;     const int k0 = (t / tn) * 32, n0 = (t % tn) * 32;
; #pragma unroll
;     for (int i = 0; i < 4; ++i) tile[(ty + 8 * i) * 33 + tx] = src[(size_t)(k0 + ty + 8 * i) * N + n0 + tx];
;     __syncthreads();
; #pragma unroll
;     for (int i = 0; i < 4; ++i) dst[(size_t)(n0 + ty + 8 * i) * K + k0 + tx] = (h16)tile[tx * 33 + ty + 8 * i];
;     __syncthreads();
;   }
; DI void conv_weights(const P& p, int l, char* smem) {
;     ...
;   convT(p.in[I_WUQ] + (size_t)l * 384 * 768, 384, 768, W + WO_UQ, tile);
.LBB0_2017:
	s_mul_hi_i32 s4, s0, 0x2aaaaaab
	s_lshr_b32 s5, s4, 31
	s_ashr_i32 s4, s4, 2
	s_add_i32 s5, s4, s5
	s_lshl_b32 s4, s5, 5
	s_mulk_i32 s5, 0xfd00
	s_add_i32 s6, s1, s5
	s_ashr_i32 s7, s6, 31
	v_add_u32_e32 v12, s4, v6
	v_lshl_add_u64 v[8:9], s[6:7], 2, v[2:3]
	v_mad_i64_i32 v[10:11], s[8:9], v12, s10, v[8:9]
	global_load_dword v10, v[10:11], off
	s_ashr_i32 s5, s4, 31
	v_add_u32_e32 v14, s6, v6
	s_add_i32 s0, s0, s72
	s_add_i32 s1, s1, s2
	s_cmpk_lt_i32 s0, 0x120
	v_add_u32_e32 v16, 8, v12
	v_mad_i64_i32 v[16:17], s[8:9], v16, s10, v[8:9]
	global_load_dword v16, v[16:17], off
	v_add_u32_e32 v18, 16, v12
	v_mad_i64_i32 v[18:19], s[8:9], v18, s10, v[8:9]
	global_load_dword v18, v[18:19], off
	v_add_u32_e32 v20, 24, v12
	v_mad_i64_i32 v[8:9], s[8:9], v20, s10, v[8:9]
	global_load_dword v8, v[8:9], off
	s_waitcnt vmcnt(0)
	ds_write_b32 v0, v10
	ds_write_b32 v0, v16 offset:1056
	ds_write_b32 v0, v18 offset:2112
	ds_write_b32 v0, v8 offset:3168
	s_waitcnt lgkmcnt(0)
	s_barrier
	ds_read2_b32 v[10:11], v7 offset1:8
	v_lshl_add_u64 v[8:9], s[4:5], 1, v[4:5]
	v_mad_i64_i32 v[12:13], s[4:5], v14, s3, v[8:9]
	s_waitcnt lgkmcnt(0)
	v_cvt_f16_f32_e32 v10, v10
	global_store_short v[12:13], v10, off
	v_cvt_f16_f32_e32 v12, v11
	v_add_u32_e32 v10, 8, v14
	v_mad_i64_i32 v[10:11], s[4:5], v10, s3, v[8:9]
	global_store_short v[10:11], v12, off
	ds_read2_b32 v[10:11], v7 offset0:16 offset1:24
	v_add_u32_e32 v12, 16, v14
	v_mad_i64_i32 v[12:13], s[4:5], v12, s3, v[8:9]
	s_waitcnt lgkmcnt(0)
	v_cvt_f16_f32_e32 v10, v10
	global_store_short v[12:13], v10, off
	v_cvt_f16_f32_e32 v10, v11
	v_add_u32_e32 v11, 24, v14
	v_mad_i64_i32 v[8:9], s[4:5], v11, s3, v[8:9]
	global_store_short v[8:9], v10, off
	s_barrier
	s_cbranch_scc1 .LBB0_2017

; DI int BIDX() { int b = blockIdx.x; asm volatile("" : "+s"(b)); return b; }
; DI void convT(const float* __restrict__ src, int K, int N, h16* __restrict__ dst, float* tile) {
;     ...
;   for (int t = BIDX(); t < nt; t += gridDim.x) {
;     const int k0 = (t / tn) * 32, n0 = (t % tn) * 32;
; #pragma unroll
;     for (int i = 0; i < 4; ++i) tile[(ty + 8 * i) * 33 + tx] = src[(size_t)(k0 + ty + 8 * i) * N + n0 + tx];
;     __syncthreads();
; #pragma unroll
;     for (int i = 0; i < 4; ++i) dst[(size_t)(n0 + ty + 8 * i) * K + k0 + tx] = (h16)tile[tx * 33 + ty + 8 * i];
;     __syncthreads();
;   }
; DI void conv_weights(const P& p, int l, char* smem) {
;     ...
;   convT(p.in[I_WUKV] + (size_t)l * 256 * 1024, 256, 1024, W + WO_UKV, tile);
.LBB0_2020:
	s_ashr_i32 s0, s4, 31
	s_lshr_b32 s0, s0, 27
	s_add_i32 s1, s4, s0
	s_and_b32 s0, s1, 0xffffffe0
	s_lshl_b32 s1, s1, 5
	s_and_b32 s1, s1, 0xfffffc00
	s_sub_i32 s6, s5, s1
	v_add_u32_e32 v8, s0, v6
	s_ashr_i32 s7, s6, 31
	v_ashrrev_i32_e32 v9, 31, v8
	v_lshl_add_u64 v[10:11], s[6:7], 2, v[2:3]
	v_lshlrev_b64 v[8:9], 12, v[8:9]
	v_lshl_add_u64 v[8:9], v[10:11], 0, v[8:9]
	global_load_dword v16, v[8:9], off
	s_ashr_i32 s1, s0, 31
	s_add_i32 s4, s4, s72
	s_add_i32 s5, s5, s2
	s_cmpk_lt_i32 s4, 0x100
	v_add_co_u32_e32 v18, vcc, s87, v8
	s_nop 1
	v_addc_co_u32_e32 v19, vcc, 0, v9, vcc
	global_load_dword v18, v[18:19], off
	v_add_co_u32_e32 v10, vcc, s3, v8
	s_nop 1
	v_addc_co_u32_e32 v11, vcc, 0, v9, vcc
	v_add_co_u32_e32 v8, vcc, s8, v8
	global_load_dword v10, v[10:11], off
	s_nop 0
	v_addc_co_u32_e32 v9, vcc, 0, v9, vcc
	global_load_dword v8, v[8:9], off
	s_waitcnt vmcnt(0)
	ds_write_b32 v0, v16
	ds_write_b32 v0, v18 offset:1056
	ds_write_b32 v0, v10 offset:2112
	ds_write_b32 v0, v8 offset:3168
	v_lshl_add_u64 v[10:11], s[0:1], 1, v[4:5]
	s_waitcnt lgkmcnt(0)
	s_barrier
	ds_read2_b32 v[12:13], v7 offset1:8
	v_add_u32_e32 v8, s6, v6
	v_ashrrev_i32_e32 v9, 31, v8
	v_lshlrev_b64 v[14:15], 9, v[8:9]
	v_lshl_add_u64 v[14:15], v[10:11], 0, v[14:15]
	s_waitcnt lgkmcnt(0)
	v_cvt_f16_f32_e32 v12, v12
	v_cvt_f16_f32_e32 v9, v13
	global_store_short v[14:15], v12, off
	v_add_u32_e32 v12, 8, v8
	v_ashrrev_i32_e32 v13, 31, v12
	v_lshlrev_b64 v[12:13], 9, v[12:13]
	v_lshl_add_u64 v[12:13], v[10:11], 0, v[12:13]
	global_store_short v[12:13], v9, off
	ds_read2_b32 v[12:13], v7 offset0:16 offset1:24
	v_add_u32_e32 v14, 16, v8
	v_ashrrev_i32_e32 v15, 31, v14
	v_lshlrev_b64 v[14:15], 9, v[14:15]
	v_lshl_add_u64 v[14:15], v[10:11], 0, v[14:15]
	s_waitcnt lgkmcnt(0)
	v_cvt_f16_f32_e32 v9, v12
	v_cvt_f16_f32_e32 v12, v13
	v_add_u32_e32 v8, 24, v8
	global_store_short v[14:15], v9, off
	v_ashrrev_i32_e32 v9, 31, v8
	v_lshlrev_b64 v[8:9], 9, v[8:9]
	v_lshl_add_u64 v[8:9], v[10:11], 0, v[8:9]
	global_store_short v[8:9], v12, off
	s_barrier
	s_cbranch_scc1 .LBB0_2020

; DI int BIDX() { int b = blockIdx.x; asm volatile("" : "+s"(b)); return b; }
; DI void convT(const float* __restrict__ src, int K, int N, h16* __restrict__ dst, float* tile) {
;     ...
;   for (int t = BIDX(); t < nt; t += gridDim.x) {
;     const int k0 = (t / tn) * 32, n0 = (t % tn) * 32;
; #pragma unroll
;     for (int i = 0; i < 4; ++i) tile[(ty + 8 * i) * 33 + tx] = src[(size_t)(k0 + ty + 8 * i) * N + n0 + tx];
;     __syncthreads();
; #pragma unroll
;     for (int i = 0; i < 4; ++i) dst[(size_t)(n0 + ty + 8 * i) * K + k0 + tx] = (h16)tile[tx * 33 + ty + 8 * i];
;     __syncthreads();
;   }
; DI void conv_weights(const P& p, int l, char* smem) {
;     ...
;   convT(p.in[I_G2] + (size_t)l * 128 * 512, 128, 512, W + WO_G2, tile);
.LBB0_2023:
	s_ashr_i32 s4, s0, 31
	s_lshr_b32 s4, s4, 28
	s_add_i32 s4, s0, s4
	s_ashr_i32 s5, s4, 4
	s_lshl_b32 s4, s5, 5
	s_lshl_b32 s5, s5, 9
	s_sub_i32 s6, s1, s5
	v_add_u32_e32 v8, s4, v6
	s_ashr_i32 s7, s6, 31
	v_ashrrev_i32_e32 v9, 31, v8
	v_lshl_add_u64 v[10:11], s[6:7], 2, v[2:3]
	v_lshlrev_b64 v[8:9], 11, v[8:9]
	v_lshl_add_u64 v[8:9], v[10:11], 0, v[8:9]
	global_load_dword v16, v[8:9], off
	s_ashr_i32 s5, s4, 31
	s_add_i32 s0, s0, s72
	s_add_i32 s1, s1, s2
	s_cmp_lt_i32 s0, 64
	v_add_co_u32_e32 v18, vcc, s3, v8
	s_nop 1
	v_addc_co_u32_e32 v19, vcc, 0, v9, vcc
	global_load_dword v18, v[18:19], off
	v_add_co_u32_e32 v10, vcc, s87, v8
	s_nop 1
	v_addc_co_u32_e32 v11, vcc, 0, v9, vcc
	v_add_co_u32_e32 v8, vcc, s8, v8
	global_load_dword v10, v[10:11], off
	s_nop 0
	v_addc_co_u32_e32 v9, vcc, 0, v9, vcc
	global_load_dword v8, v[8:9], off
	s_waitcnt vmcnt(0)
	ds_write_b32 v0, v16
	ds_write_b32 v0, v18 offset:1056
	ds_write_b32 v0, v10 offset:2112
	ds_write_b32 v0, v8 offset:3168
	v_lshl_add_u64 v[10:11], s[4:5], 1, v[4:5]
	s_waitcnt lgkmcnt(0)
	s_barrier
	ds_read2_b32 v[12:13], v7 offset1:8
	v_add_u32_e32 v8, s6, v6
	v_ashrrev_i32_e32 v9, 31, v8
	v_lshlrev_b64 v[14:15], 8, v[8:9]
	v_lshl_add_u64 v[14:15], v[10:11], 0, v[14:15]
	s_waitcnt lgkmcnt(0)
	v_cvt_f16_f32_e32 v12, v12
	v_cvt_f16_f32_e32 v9, v13
	global_store_short v[14:15], v12, off
	v_add_u32_e32 v12, 8, v8
	v_ashrrev_i32_e32 v13, 31, v12
	v_lshlrev_b64 v[12:13], 8, v[12:13]
	v_lshl_add_u64 v[12:13], v[10:11], 0, v[12:13]
	global_store_short v[12:13], v9, off
	ds_read2_b32 v[12:13], v7 offset0:16 offset1:24
	v_add_u32_e32 v14, 16, v8
	v_ashrrev_i32_e32 v15, 31, v14
	v_lshlrev_b64 v[14:15], 8, v[14:15]
	v_lshl_add_u64 v[14:15], v[10:11], 0, v[14:15]
	s_waitcnt lgkmcnt(0)
	v_cvt_f16_f32_e32 v9, v12
	v_cvt_f16_f32_e32 v12, v13
	v_add_u32_e32 v8, 24, v8
	global_store_short v[14:15], v9, off
	v_ashrrev_i32_e32 v9, 31, v8
	v_lshlrev_b64 v[8:9], 8, v[8:9]
	v_lshl_add_u64 v[8:9], v[10:11], 0, v[8:9]
	global_store_short v[8:9], v12, off
	s_barrier
	s_cbranch_scc1 .LBB0_2023

; DI int BIDX() { int b = blockIdx.x; asm volatile("" : "+s"(b)); return b; }
; DI void convT(const float* __restrict__ src, int K, int N, h16* __restrict__ dst, float* tile) {
;     ...
;   for (int t = BIDX(); t < nt; t += gridDim.x) {
;     const int k0 = (t / tn) * 32, n0 = (t % tn) * 32;
; #pragma unroll
;     for (int i = 0; i < 4; ++i) tile[(ty + 8 * i) * 33 + tx] = src[(size_t)(k0 + ty + 8 * i) * N + n0 + tx];
;     __syncthreads();
; #pragma unroll
;     for (int i = 0; i < 4; ++i) dst[(size_t)(n0 + ty + 8 * i) * K + k0 + tx] = (h16)tile[tx * 33 + ty + 8 * i];
;     __syncthreads();
;   }
; DI void conv_weights(const P& p, int l, char* smem) {
;     ...
;   for (int n = 0; n < 3; ++n) convT(p.in[I_WB] + ((size_t)l * 3 + n) * 512 * 1024, 512, 1024, W + WO_WB + (size_t)n * 1024 * 512, tile);
.LBB0_2026:
	s_ashr_i32 s0, s4, 31
	s_lshr_b32 s0, s0, 27
	s_add_i32 s1, s4, s0
	s_and_b32 s0, s1, 0xffffffe0
	s_lshl_b32 s1, s1, 5
	s_and_b32 s1, s1, 0xfffffc00
	s_sub_i32 s8, s6, s1
	v_add_u32_e32 v8, s0, v6
	s_ashr_i32 s9, s8, 31
	v_ashrrev_i32_e32 v9, 31, v8
	v_lshl_add_u64 v[10:11], s[8:9], 2, v[2:3]
	v_lshlrev_b64 v[8:9], 12, v[8:9]
	v_lshl_add_u64 v[8:9], v[10:11], 0, v[8:9]
	global_load_dword v16, v[8:9], off
	s_ashr_i32 s1, s0, 31
	s_add_i32 s4, s4, s5
	s_add_i32 s6, s6, s7
	s_cmpk_lt_i32 s4, 0x200
	v_add_co_u32_e32 v18, vcc, s87, v8
	s_nop 1
	v_addc_co_u32_e32 v19, vcc, 0, v9, vcc
	global_load_dword v18, v[18:19], off
	v_add_co_u32_e32 v10, vcc, s2, v8
	s_nop 1
	v_addc_co_u32_e32 v11, vcc, 0, v9, vcc
	v_add_co_u32_e32 v8, vcc, s3, v8
	global_load_dword v10, v[10:11], off
	s_nop 0
	v_addc_co_u32_e32 v9, vcc, 0, v9, vcc
	global_load_dword v8, v[8:9], off
	s_waitcnt vmcnt(0)
	ds_write_b32 v0, v16
	ds_write_b32 v0, v18 offset:1056
	ds_write_b32 v0, v10 offset:2112
	ds_write_b32 v0, v8 offset:3168
	v_lshl_add_u64 v[10:11], s[0:1], 1, v[4:5]
	s_waitcnt lgkmcnt(0)
	s_barrier
	ds_read2_b32 v[12:13], v7 offset1:8
	v_add_u32_e32 v8, s8, v6
	v_ashrrev_i32_e32 v9, 31, v8
	v_lshlrev_b64 v[14:15], 10, v[8:9]
	v_lshl_add_u64 v[14:15], v[10:11], 0, v[14:15]
	s_waitcnt lgkmcnt(0)
	v_cvt_f16_f32_e32 v12, v12
	v_cvt_f16_f32_e32 v9, v13
	global_store_short v[14:15], v12, off
	v_add_u32_e32 v12, 8, v8
	v_ashrrev_i32_e32 v13, 31, v12
	v_lshlrev_b64 v[12:13], 10, v[12:13]
	v_lshl_add_u64 v[12:13], v[10:11], 0, v[12:13]
	global_store_short v[12:13], v9, off
	ds_read2_b32 v[12:13], v7 offset0:16 offset1:24
	v_add_u32_e32 v14, 16, v8
	v_ashrrev_i32_e32 v15, 31, v14
	v_lshlrev_b64 v[14:15], 10, v[14:15]
	v_lshl_add_u64 v[14:15], v[10:11], 0, v[14:15]
	s_waitcnt lgkmcnt(0)
	v_cvt_f16_f32_e32 v9, v12
	v_cvt_f16_f32_e32 v12, v13
	v_add_u32_e32 v8, 24, v8
	global_store_short v[14:15], v9, off
	v_ashrrev_i32_e32 v9, 31, v8
	v_lshlrev_b64 v[8:9], 10, v[8:9]
	v_lshl_add_u64 v[8:9], v[10:11], 0, v[8:9]
	global_store_short v[8:9], v12, off
	s_barrier
	s_cbranch_scc1 .LBB0_2026

; DI int TIDX() { int t = threadIdx.x; asm volatile("" : "+v"(t)); return t; }
; DI int BIDX() { int b = blockIdx.x; asm volatile("" : "+s"(b)); return b; }
; DI void convT(const float* __restrict__ src, int K, int N, h16* __restrict__ dst, float* tile) {
;   const int tid = TIDX(), tx = tid & 31, ty = tid >> 5;
;   const int tn = N >> 5, nt = (K >> 5) * tn;
;   for (int t = BIDX(); t < nt; t += gridDim.x) {
;     const int k0 = (t / tn) * 32, n0 = (t % tn) * 32;
; #pragma unroll
;     for (int i = 0; i < 4; ++i) tile[(ty + 8 * i) * 33 + tx] = src[(size_t)(k0 + ty + 8 * i) * N + n0 + tx];
;     __syncthreads();
; #pragma unroll
;     for (int i = 0; i < 4; ++i) dst[(size_t)(n0 + ty + 8 * i) * K + k0 + tx] = (h16)tile[tx * 33 + ty + 8 * i];
;     __syncthreads();
;   }
; }
; DI void conv_weights(const P& p, int l, char* smem) {
;     ...
;   convT(p.in[I_WOUT] + (size_t)l * 1024 * 1024, 1024, 1024, W + WO_WOUT, tile);
.LBB0_2035:
	s_ashr_i32 s0, s4, 31
	s_lshr_b32 s0, s0, 27
	s_add_i32 s1, s4, s0
	s_and_b32 s0, s1, 0xffffffe0
	s_lshl_b32 s1, s1, 5
	s_and_b32 s1, s1, 0xfffffc00
	s_sub_i32 s8, s6, s1
	v_add_u32_e32 v8, s0, v6
	s_ashr_i32 s9, s8, 31
	v_ashrrev_i32_e32 v9, 31, v8
	v_lshl_add_u64 v[10:11], s[8:9], 2, v[2:3]
	v_lshlrev_b64 v[8:9], 12, v[8:9]
	v_lshl_add_u64 v[8:9], v[10:11], 0, v[8:9]
	global_load_dword v16, v[8:9], off
	s_ashr_i32 s1, s0, 31
	s_add_i32 s4, s4, s5
	s_add_i32 s6, s6, s7
	s_cmpk_lt_i32 s4, 0x400
	v_add_co_u32_e32 v18, vcc, s87, v8
	s_nop 1
	v_addc_co_u32_e32 v19, vcc, 0, v9, vcc
	global_load_dword v18, v[18:19], off
	v_add_co_u32_e32 v10, vcc, s2, v8
	s_nop 1
	v_addc_co_u32_e32 v11, vcc, 0, v9, vcc
	v_add_co_u32_e32 v8, vcc, s3, v8
	global_load_dword v10, v[10:11], off
	s_nop 0
	v_addc_co_u32_e32 v9, vcc, 0, v9, vcc
	global_load_dword v8, v[8:9], off
	s_waitcnt vmcnt(0)
	ds_write_b32 v0, v16
	ds_write_b32 v0, v18 offset:1056
	ds_write_b32 v0, v10 offset:2112
	ds_write_b32 v0, v8 offset:3168
	v_lshl_add_u64 v[10:11], s[0:1], 1, v[4:5]
	s_waitcnt lgkmcnt(0)
	s_barrier
	ds_read2_b32 v[12:13], v7 offset1:8
	v_add_u32_e32 v8, s8, v6
	v_ashrrev_i32_e32 v9, 31, v8
	v_lshlrev_b64 v[14:15], 11, v[8:9]
	v_lshl_add_u64 v[14:15], v[10:11], 0, v[14:15]
	s_waitcnt lgkmcnt(0)
	v_cvt_f16_f32_e32 v12, v12
	v_cvt_f16_f32_e32 v9, v13
	global_store_short v[14:15], v12, off
	v_add_u32_e32 v12, 8, v8
	v_ashrrev_i32_e32 v13, 31, v12
	v_lshlrev_b64 v[12:13], 11, v[12:13]
	v_lshl_add_u64 v[12:13], v[10:11], 0, v[12:13]
	global_store_short v[12:13], v9, off
	ds_read2_b32 v[12:13], v7 offset0:16 offset1:24
	v_add_u32_e32 v14, 16, v8
	v_ashrrev_i32_e32 v15, 31, v14
	v_lshlrev_b64 v[14:15], 11, v[14:15]
	v_lshl_add_u64 v[14:15], v[10:11], 0, v[14:15]
	s_waitcnt lgkmcnt(0)
	v_cvt_f16_f32_e32 v9, v12
	v_cvt_f16_f32_e32 v12, v13
	v_add_u32_e32 v8, 24, v8
	global_store_short v[14:15], v9, off
	v_ashrrev_i32_e32 v9, 31, v8
	v_lshlrev_b64 v[8:9], 11, v[8:9]
	v_lshl_add_u64 v[8:9], v[10:11], 0, v[8:9]
	global_store_short v[8:9], v12, off
	s_barrier
	s_cbranch_scc1 .LBB0_2035

; DI int TIDX() { int t = threadIdx.x; asm volatile("" : "+v"(t)); return t; }
; DI int BIDX() { int b = blockIdx.x; asm volatile("" : "+s"(b)); return b; }
; DI void convT(const float* __restrict__ src, int K, int N, h16* __restrict__ dst, float* tile) {
;   const int tid = TIDX(), tx = tid & 31, ty = tid >> 5;
;   const int tn = N >> 5, nt = (K >> 5) * tn;
;   for (int t = BIDX(); t < nt; t += gridDim.x) {
;     const int k0 = (t / tn) * 32, n0 = (t % tn) * 32;
; #pragma unroll
;     for (int i = 0; i < 4; ++i) tile[(ty + 8 * i) * 33 + tx] = src[(size_t)(k0 + ty + 8 * i) * N + n0 + tx];
;     __syncthreads();
; #pragma unroll
;     for (int i = 0; i < 4; ++i) dst[(size_t)(n0 + ty + 8 * i) * K + k0 + tx] = (h16)tile[tx * 33 + ty + 8 * i];
;     __syncthreads();
;   }
; }
; DI void conv_weights(const P& p, int l, char* smem) {
;     ...
;   convT(p.in[I_FIN] + (size_t)l * 1024 * 5632, 1024, 5632, W + WO_FIN, tile);
.LBB0_2038:
	s_mul_hi_i32 s6, s0, 0x2e8ba2e9
	s_lshr_b32 s7, s6, 31
	s_ashr_i32 s6, s6, 5
	s_add_i32 s7, s6, s7
	s_lshl_b32 s6, s7, 5
	s_mulk_i32 s7, 0xea00
	s_add_i32 s8, s4, s7
	s_ashr_i32 s9, s8, 31
	v_add_u32_e32 v12, s6, v6
	v_lshl_add_u64 v[8:9], s[8:9], 2, v[2:3]
	v_mad_i64_i32 v[10:11], s[10:11], v12, s2, v[8:9]
	global_load_dword v10, v[10:11], off
	s_ashr_i32 s7, s6, 31
	s_add_i32 s0, s0, s1
	s_add_i32 s4, s4, s5
	s_cmpk_lt_i32 s0, 0x1600
	v_add_u32_e32 v16, 8, v12
	v_mad_i64_i32 v[16:17], s[10:11], v16, s2, v[8:9]
	global_load_dword v16, v[16:17], off
	v_add_u32_e32 v18, 16, v12
	v_mad_i64_i32 v[18:19], s[10:11], v18, s2, v[8:9]
	global_load_dword v18, v[18:19], off
	v_add_u32_e32 v20, 24, v12
	v_mad_i64_i32 v[8:9], s[10:11], v20, s2, v[8:9]
	global_load_dword v8, v[8:9], off
	s_waitcnt vmcnt(0)
	ds_write_b32 v0, v10
	ds_write_b32 v0, v16 offset:1056
	ds_write_b32 v0, v18 offset:2112
	ds_write_b32 v0, v8 offset:3168
	v_lshl_add_u64 v[10:11], s[6:7], 1, v[4:5]
	s_waitcnt lgkmcnt(0)
	s_barrier
	ds_read2_b32 v[12:13], v7 offset1:8
	v_add_u32_e32 v8, s8, v6
	v_ashrrev_i32_e32 v9, 31, v8
	v_lshlrev_b64 v[14:15], 11, v[8:9]
	v_lshl_add_u64 v[14:15], v[10:11], 0, v[14:15]
	s_waitcnt lgkmcnt(0)
	v_cvt_f16_f32_e32 v12, v12
	v_cvt_f16_f32_e32 v9, v13
	global_store_short v[14:15], v12, off
	v_add_u32_e32 v12, 8, v8
	v_ashrrev_i32_e32 v13, 31, v12
	v_lshlrev_b64 v[12:13], 11, v[12:13]
	v_lshl_add_u64 v[12:13], v[10:11], 0, v[12:13]
	global_store_short v[12:13], v9, off
	ds_read2_b32 v[12:13], v7 offset0:16 offset1:24
	v_add_u32_e32 v14, 16, v8
	v_ashrrev_i32_e32 v15, 31, v14
	v_lshlrev_b64 v[14:15], 11, v[14:15]
	v_lshl_add_u64 v[14:15], v[10:11], 0, v[14:15]
	s_waitcnt lgkmcnt(0)
	v_cvt_f16_f32_e32 v9, v12
	v_cvt_f16_f32_e32 v12, v13
	v_add_u32_e32 v8, 24, v8
	global_store_short v[14:15], v9, off
	v_ashrrev_i32_e32 v9, 31, v8
	v_lshlrev_b64 v[8:9], 11, v[8:9]
	v_lshl_add_u64 v[8:9], v[10:11], 0, v[8:9]
	global_store_short v[8:9], v12, off
	s_barrier
	s_cbranch_scc1 .LBB0_2038

; DI int TIDX() { int t = threadIdx.x; asm volatile("" : "+v"(t)); return t; }
; DI int BIDX() { int b = blockIdx.x; asm volatile("" : "+s"(b)); return b; }
; DI void convT(const float* __restrict__ src, int K, int N, h16* __restrict__ dst, float* tile) {
;   const int tid = TIDX(), tx = tid & 31, ty = tid >> 5;
;   const int tn = N >> 5, nt = (K >> 5) * tn;
;   for (int t = BIDX(); t < nt; t += gridDim.x) {
;     const int k0 = (t / tn) * 32, n0 = (t % tn) * 32;
; #pragma unroll
;     for (int i = 0; i < 4; ++i) tile[(ty + 8 * i) * 33 + tx] = src[(size_t)(k0 + ty + 8 * i) * N + n0 + tx];
;     __syncthreads();
; #pragma unroll
;     for (int i = 0; i < 4; ++i) dst[(size_t)(n0 + ty + 8 * i) * K + k0 + tx] = (h16)tile[tx * 33 + ty + 8 * i];
;     __syncthreads();
;   }
; }
; DI void conv_weights(const P& p, int l, char* smem) {
;     ...
;   convT(p.in[I_FOUT] + (size_t)l * 2816 * 1024, 2816, 1024, W + WO_FOUT, tile);
.LBB0_2041:
	s_ashr_i32 s0, s4, 31
	s_lshr_b32 s0, s0, 27
	s_add_i32 s1, s4, s0
	s_and_b32 s0, s1, 0xffffffe0
	s_lshl_b32 s1, s1, 5
	s_and_b32 s1, s1, 0xfffffc00
	s_sub_i32 s8, s6, s1
	v_add_u32_e32 v8, s0, v6
	s_ashr_i32 s9, s8, 31
	v_ashrrev_i32_e32 v9, 31, v8
	v_lshl_add_u64 v[10:11], s[8:9], 2, v[2:3]
	v_lshlrev_b64 v[8:9], 12, v[8:9]
	v_lshl_add_u64 v[8:9], v[10:11], 0, v[8:9]
	global_load_dword v16, v[8:9], off
	s_ashr_i32 s1, s0, 31
	v_add_u32_e32 v14, s8, v6
	s_add_i32 s4, s4, s5
	s_add_i32 s6, s6, s7
	s_cmpk_gt_i32 s4, 0xaff
	v_add_co_u32_e32 v18, vcc, s87, v8
	s_nop 1
	v_addc_co_u32_e32 v19, vcc, 0, v9, vcc
	global_load_dword v18, v[18:19], off
	v_add_co_u32_e32 v10, vcc, s2, v8
	s_nop 1
	v_addc_co_u32_e32 v11, vcc, 0, v9, vcc
	v_add_co_u32_e32 v8, vcc, s3, v8
	global_load_dword v10, v[10:11], off
	s_nop 0
	v_addc_co_u32_e32 v9, vcc, 0, v9, vcc
	global_load_dword v8, v[8:9], off
	s_waitcnt vmcnt(0)
	ds_write_b32 v0, v16
	ds_write_b32 v0, v18 offset:1056
	ds_write_b32 v0, v10 offset:2112
	ds_write_b32 v0, v8 offset:3168
	s_waitcnt lgkmcnt(0)
	s_barrier
	ds_read2_b32 v[10:11], v7 offset1:8
	v_lshl_add_u64 v[8:9], s[0:1], 1, v[4:5]
	v_mad_i64_i32 v[12:13], s[0:1], v14, s10, v[8:9]
	s_waitcnt lgkmcnt(0)
	v_cvt_f16_f32_e32 v10, v10
	global_store_short v[12:13], v10, off
	v_cvt_f16_f32_e32 v12, v11
	v_add_u32_e32 v10, 8, v14
	v_mad_i64_i32 v[10:11], s[0:1], v10, s10, v[8:9]
	global_store_short v[10:11], v12, off
	ds_read2_b32 v[10:11], v7 offset0:16 offset1:24
	v_add_u32_e32 v12, 16, v14
	v_mad_i64_i32 v[12:13], s[0:1], v12, s10, v[8:9]
	s_waitcnt lgkmcnt(0)
	v_cvt_f16_f32_e32 v10, v10
	global_store_short v[12:13], v10, off
	v_cvt_f16_f32_e32 v10, v11
	v_add_u32_e32 v11, 24, v14
	v_mad_i64_i32 v[8:9], s[0:1], v11, s10, v[8:9]
	global_store_short v[8:9], v10, off
	s_barrier
	s_cbranch_scc0 .LBB0_2041
